# xcc-local barrier: L1 invalidate issued right behind the arrival atomic (overlaps the wait), + rowpass prefetch
# speedup vs baseline: 1.0062x; 1.0062x over previous
.LBB0_411:
	s_and_b64 vcc, exec, s[2:3]
	s_cbranch_vccz .LBB0_429
	s_waitcnt vmcnt(0)
	s_waitcnt vmcnt(0)
	s_barrier
	s_and_saveexec_b64 s[2:3], s[0:1]
	s_cbranch_execz .LBB0_428
	v_readlane_b32 s0, v253, 9
	s_lshl_b32 s0, s0, 8
	v_readlane_b32 s6, v253, 3
	v_readlane_b32 s7, v253, 4
	s_add_u32 s0, s6, s0
	s_addc_u32 s1, s7, 0
	v_mov_b32_e32 v2, 0x3000
	v_mov_b32_e32 v3, 1
	s_waitcnt vmcnt(0) expcnt(0) lgkmcnt(0)
	global_atomic_add v4, v2, v3, s[0:1] offset:1792 sc0
	buffer_inv sc1
	s_add_u32 s6, s0, 0x4700
	s_addc_u32 s7, s1, 0
	s_mov_b64 s[8:9], -1
	s_waitcnt vmcnt(1)
	v_and_b32_e32 v2, 31, v4
	v_cmp_ne_u32_e32 vcc, 31, v2
	v_mov_b64_e32 v[2:3], s[6:7]
	s_and_saveexec_b64 s[0:1], vcc
	s_cbranch_execz .LBB0_425
	v_mov_b32_e32 v2, 0
	global_load_dword v5, v2, s[6:7] sc1
	v_lshrrev_b32_e32 v3, 5, v4
	s_mov_b64 s[12:13], 0
	s_waitcnt vmcnt(0)
	v_cmp_eq_u32_e32 vcc, v5, v3
	s_and_saveexec_b64 s[10:11], vcc
	s_cbranch_execz .LBB0_424
	s_add_u32 s8, s78, 0x4200
	s_addc_u32 s9, s79, 0
	s_mov_b32 s22, 1
	s_branch .LBB0_417

.LBB0_427:
	s_or_b64 exec, exec, s[0:1]
	s_waitcnt vmcnt(0)
	s_waitcnt vmcnt(0)

.LBB0_458:
	s_cmp_gt_i32 s89, 2
	s_cselect_b64 s[0:1], -1, 0
	s_and_b64 s[2:3], s[4:5], s[0:1]
	s_andn2_b64 vcc, exec, s[2:3]
	s_cbranch_vccnz .LBB0_476
	s_waitcnt vmcnt(0)
	v_cmp_eq_u32_e32 vcc, 0, v0
	s_waitcnt vmcnt(0)
	s_barrier
	s_and_saveexec_b64 s[2:3], vcc
	s_cbranch_execz .LBB0_475
	v_readlane_b32 s4, v253, 9
	s_lshl_b32 s4, s4, 8
	v_readlane_b32 s6, v253, 3
	v_readlane_b32 s7, v253, 4
	s_add_u32 s4, s6, s4
	s_addc_u32 s5, s7, 0
	v_mov_b32_e32 v2, 0x3000
	v_mov_b32_e32 v3, 1
	s_waitcnt vmcnt(0) expcnt(0) lgkmcnt(0)
	global_atomic_add v4, v2, v3, s[4:5] offset:1792 sc0
	buffer_inv sc1
	s_add_u32 s6, s4, 0x4700
	s_addc_u32 s7, s5, 0
	s_mov_b64 s[8:9], -1
	s_waitcnt vmcnt(1)
	v_and_b32_e32 v2, 31, v4
	v_cmp_ne_u32_e32 vcc, 31, v2
	v_mov_b64_e32 v[2:3], s[6:7]
	s_and_saveexec_b64 s[4:5], vcc
	s_cbranch_execz .LBB0_472
	v_mov_b32_e32 v2, 0
	global_load_dword v5, v2, s[6:7] sc1
	v_lshrrev_b32_e32 v3, 5, v4
	s_mov_b64 s[12:13], 0
	s_waitcnt vmcnt(0)
	v_cmp_eq_u32_e32 vcc, v5, v3
	s_and_saveexec_b64 s[10:11], vcc
	s_cbranch_execz .LBB0_471
	s_add_u32 s8, s78, 0x4200
	s_addc_u32 s9, s79, 0
	s_mov_b32 s22, 1
	s_branch .LBB0_464

.LBB0_474:
	s_or_b64 exec, exec, s[4:5]
	s_waitcnt vmcnt(0)
	s_waitcnt vmcnt(0)

.LBB0_502:
	s_cmp_gt_i32 s89, 3
	s_cselect_b64 s[2:3], -1, 0
	s_and_b64 s[0:1], s[0:1], s[2:3]
	s_andn2_b64 vcc, exec, s[0:1]
	s_cbranch_vccnz .LBB0_520
	s_waitcnt vmcnt(0)
	v_cmp_eq_u32_e32 vcc, 0, v0
	s_waitcnt vmcnt(0)
	s_barrier
	s_and_saveexec_b64 s[0:1], vcc
	s_cbranch_execz .LBB0_519
	v_readlane_b32 s4, v253, 9
	s_lshl_b32 s4, s4, 8
	v_readlane_b32 s6, v253, 3
	v_readlane_b32 s7, v253, 4
	s_add_u32 s4, s6, s4
	s_addc_u32 s5, s7, 0
	v_mov_b32_e32 v2, 0x3000
	v_mov_b32_e32 v3, 1
	s_waitcnt vmcnt(0) expcnt(0) lgkmcnt(0)
	global_atomic_add v4, v2, v3, s[4:5] offset:1792 sc0
	buffer_inv sc1
	s_add_u32 s6, s4, 0x4700
	s_addc_u32 s7, s5, 0
	s_mov_b64 s[8:9], -1
	s_waitcnt vmcnt(1)
	v_and_b32_e32 v2, 31, v4
	v_cmp_ne_u32_e32 vcc, 31, v2
	v_mov_b64_e32 v[2:3], s[6:7]
	s_and_saveexec_b64 s[4:5], vcc
	s_cbranch_execz .LBB0_516
	v_mov_b32_e32 v2, 0
	global_load_dword v5, v2, s[6:7] sc1
	v_lshrrev_b32_e32 v3, 5, v4
	s_mov_b64 s[12:13], 0
	s_waitcnt vmcnt(0)
	v_cmp_eq_u32_e32 vcc, v5, v3
	s_and_saveexec_b64 s[10:11], vcc
	s_cbranch_execz .LBB0_515
	s_add_u32 s8, s78, 0x4200
	s_addc_u32 s9, s79, 0
	s_mov_b32 s22, 1
	s_branch .LBB0_508

.LBB0_526:
	s_cmp_gt_i32 s89, 4
	s_cselect_b64 s[0:1], -1, 0
	s_and_b64 s[2:3], s[6:7], s[0:1]
	s_andn2_b64 vcc, exec, s[2:3]
	s_cbranch_vccnz .LBB0_544
	s_waitcnt vmcnt(0)
	v_cmp_eq_u32_e32 vcc, 0, v0
	s_waitcnt vmcnt(0)
	s_barrier
	s_and_saveexec_b64 s[2:3], vcc
	s_cbranch_execz .LBB0_543
	v_readlane_b32 s4, v253, 9
	s_lshl_b32 s4, s4, 8
	v_readlane_b32 s6, v253, 3
	v_readlane_b32 s7, v253, 4
	s_add_u32 s4, s6, s4
	s_addc_u32 s5, s7, 0
	v_mov_b32_e32 v2, 0x3000
	v_mov_b32_e32 v3, 1
	s_waitcnt vmcnt(0) expcnt(0) lgkmcnt(0)
	global_atomic_add v4, v2, v3, s[4:5] offset:1792 sc0
	buffer_inv sc1
	s_add_u32 s6, s4, 0x4700
	s_addc_u32 s7, s5, 0
	s_mov_b64 s[8:9], -1
	s_waitcnt vmcnt(1)
	v_and_b32_e32 v2, 31, v4
	v_cmp_ne_u32_e32 vcc, 31, v2
	v_mov_b64_e32 v[2:3], s[6:7]
	s_and_saveexec_b64 s[4:5], vcc
	s_cbranch_execz .LBB0_540
	v_mov_b32_e32 v2, 0
	global_load_dword v5, v2, s[6:7] sc1
	v_lshrrev_b32_e32 v3, 5, v4
	s_mov_b64 s[12:13], 0
	s_waitcnt vmcnt(0)
	v_cmp_eq_u32_e32 vcc, v5, v3
	s_and_saveexec_b64 s[10:11], vcc
	s_cbranch_execz .LBB0_539
	s_add_u32 s8, s78, 0x4200
	s_addc_u32 s9, s79, 0
	s_mov_b32 s22, 1
	s_branch .LBB0_532

.LBB0_605:
	s_cmp_gt_i32 s89, 5
	s_cselect_b64 s[0:1], -1, 0
	s_and_b64 s[2:3], s[4:5], s[0:1]
	s_andn2_b64 vcc, exec, s[2:3]
	s_cbranch_vccnz .LBB0_623
	s_waitcnt vmcnt(0)
	v_cmp_eq_u32_e32 vcc, 0, v0
	s_waitcnt vmcnt(0)
	s_barrier
	s_and_saveexec_b64 s[2:3], vcc
	s_cbranch_execz .LBB0_622
	v_readlane_b32 s4, v253, 9
	s_lshl_b32 s4, s4, 8
	v_readlane_b32 s6, v253, 3
	v_readlane_b32 s7, v253, 4
	s_add_u32 s4, s6, s4
	s_addc_u32 s5, s7, 0
	v_mov_b32_e32 v2, 0x3000
	v_mov_b32_e32 v3, 1
	s_waitcnt vmcnt(0) expcnt(0) lgkmcnt(0)
	global_atomic_add v4, v2, v3, s[4:5] offset:1792 sc0
	buffer_inv sc1
	s_add_u32 s6, s4, 0x4700
	s_addc_u32 s7, s5, 0
	s_mov_b64 s[8:9], -1
	s_waitcnt vmcnt(1)
	v_and_b32_e32 v2, 31, v4
	v_cmp_ne_u32_e32 vcc, 31, v2
	v_mov_b64_e32 v[2:3], s[6:7]
	s_and_saveexec_b64 s[4:5], vcc
	s_cbranch_execz .LBB0_619
	v_mov_b32_e32 v2, 0
	global_load_dword v5, v2, s[6:7] sc1
	v_lshrrev_b32_e32 v3, 5, v4
	s_mov_b64 s[12:13], 0
	s_waitcnt vmcnt(0)
	v_cmp_eq_u32_e32 vcc, v5, v3
	s_and_saveexec_b64 s[10:11], vcc
	s_cbranch_execz .LBB0_618
	s_add_u32 s8, s78, 0x4200
	s_addc_u32 s9, s79, 0
	s_mov_b32 s22, 1
	s_branch .LBB0_611

.LBB0_717:
	s_cmp_gt_i32 s89, 6
	v_readlane_b32 s2, v252, 12
	s_cselect_b64 s[0:1], -1, 0
	v_readlane_b32 s3, v252, 13
	s_and_b64 s[2:3], s[2:3], s[0:1]
	s_andn2_b64 vcc, exec, s[2:3]
	s_cbranch_vccnz .LBB0_735
	s_waitcnt vmcnt(0)
	v_cmp_eq_u32_e32 vcc, 0, v0
	s_waitcnt vmcnt(0)
	s_barrier
	s_and_saveexec_b64 s[2:3], vcc
	s_cbranch_execz .LBB0_734
	v_readlane_b32 s4, v253, 9
	s_lshl_b32 s4, s4, 8
	v_readlane_b32 s6, v253, 3
	v_readlane_b32 s7, v253, 4
	s_add_u32 s4, s6, s4
	s_addc_u32 s5, s7, 0
	v_mov_b32_e32 v1, 0x3000
	v_mov_b32_e32 v2, 1
	s_waitcnt vmcnt(0) expcnt(0) lgkmcnt(0)
	global_atomic_add v4, v1, v2, s[4:5] offset:1792 sc0
	buffer_inv sc1
	s_add_u32 s6, s4, 0x4700
	s_addc_u32 s7, s5, 0
	s_mov_b64 s[8:9], -1
	v_mov_b64_e32 v[2:3], s[6:7]
	s_waitcnt vmcnt(1)
	v_and_b32_e32 v1, 31, v4
	v_cmp_ne_u32_e32 vcc, 31, v1
	s_and_saveexec_b64 s[4:5], vcc
	s_cbranch_execz .LBB0_731
	v_mov_b32_e32 v1, 0
	global_load_dword v3, v1, s[6:7] sc1
	v_lshrrev_b32_e32 v2, 5, v4
	s_mov_b64 s[12:13], 0
	s_waitcnt vmcnt(0)
	v_cmp_eq_u32_e32 vcc, v3, v2
	s_and_saveexec_b64 s[10:11], vcc
	s_cbranch_execz .LBB0_730
	s_add_u32 s8, s78, 0x4200
	s_addc_u32 s9, s79, 0
	s_mov_b32 s22, 1
	s_branch .LBB0_723

.LBB0_739:
	s_cmp_gt_i32 s89, 7
	s_cselect_b64 s[2:3], -1, 0
	s_and_b64 s[0:1], s[0:1], s[2:3]
	s_andn2_b64 vcc, exec, s[0:1]
	s_cbranch_vccnz .LBB0_757
	s_waitcnt vmcnt(0)
	v_cmp_eq_u32_e32 vcc, 0, v0
	s_waitcnt vmcnt(0)
	s_barrier
	s_and_saveexec_b64 s[0:1], vcc
	s_cbranch_execz .LBB0_756
	v_readlane_b32 s4, v253, 9
	s_lshl_b32 s4, s4, 8
	v_readlane_b32 s6, v253, 3
	v_readlane_b32 s7, v253, 4
	s_add_u32 s4, s6, s4
	s_addc_u32 s5, s7, 0
	v_mov_b32_e32 v1, 0x3000
	v_mov_b32_e32 v2, 1
	s_waitcnt vmcnt(0) expcnt(0) lgkmcnt(0)
	global_atomic_add v4, v1, v2, s[4:5] offset:1792 sc0
	buffer_inv sc1
	s_add_u32 s6, s4, 0x4700
	s_addc_u32 s7, s5, 0
	s_mov_b64 s[8:9], -1
	v_mov_b64_e32 v[2:3], s[6:7]
	s_waitcnt vmcnt(1)
	v_and_b32_e32 v1, 31, v4
	v_cmp_ne_u32_e32 vcc, 31, v1
	s_and_saveexec_b64 s[4:5], vcc
	s_cbranch_execz .LBB0_753
	v_mov_b32_e32 v1, 0
	global_load_dword v3, v1, s[6:7] sc1
	v_lshrrev_b32_e32 v2, 5, v4
	s_mov_b64 s[12:13], 0
	s_waitcnt vmcnt(0)
	v_cmp_eq_u32_e32 vcc, v3, v2
	s_and_saveexec_b64 s[10:11], vcc
	s_cbranch_execz .LBB0_752
	s_add_u32 s8, s78, 0x4200
	s_addc_u32 s9, s79, 0
	s_mov_b32 s22, 1
	s_branch .LBB0_745

.LBB0_1061:
	s_cmp_gt_i32 s89, 8
	s_cselect_b64 s[0:1], -1, 0
	s_and_b64 s[2:3], s[38:39], s[0:1]
	s_andn2_b64 vcc, exec, s[2:3]
	s_cbranch_vccnz .LBB0_1079
	s_waitcnt vmcnt(0)
	v_cmp_eq_u32_e32 vcc, 0, v0
	s_waitcnt vmcnt(0)
	s_barrier
	s_and_saveexec_b64 s[2:3], vcc
	s_cbranch_execz .LBB0_1078
	v_readlane_b32 s4, v253, 9
	s_lshl_b32 s4, s4, 8
	v_readlane_b32 s6, v253, 3
	v_readlane_b32 s7, v253, 4
	s_add_u32 s4, s6, s4
	s_addc_u32 s5, s7, 0
	v_mov_b32_e32 v1, 0x3000
	v_mov_b32_e32 v2, 1
	s_waitcnt vmcnt(0) expcnt(0) lgkmcnt(0)
	global_atomic_add v4, v1, v2, s[4:5] offset:1792 sc0
	buffer_inv sc1
	s_add_u32 s6, s4, 0x4700
	s_addc_u32 s7, s5, 0
	s_mov_b64 s[8:9], -1
	v_mov_b64_e32 v[2:3], s[6:7]
	s_waitcnt vmcnt(1)
	v_and_b32_e32 v1, 31, v4
	v_cmp_ne_u32_e32 vcc, 31, v1
	s_and_saveexec_b64 s[4:5], vcc
	s_cbranch_execz .LBB0_1075
	v_mov_b32_e32 v1, 0
	global_load_dword v3, v1, s[6:7] sc1
	v_lshrrev_b32_e32 v2, 5, v4
	s_mov_b64 s[12:13], 0
	s_waitcnt vmcnt(0)
	v_cmp_eq_u32_e32 vcc, v3, v2
	s_and_saveexec_b64 s[10:11], vcc
	s_cbranch_execz .LBB0_1074
	s_add_u32 s8, s78, 0x4200
	s_addc_u32 s9, s79, 0
	s_mov_b32 s22, 1
	s_branch .LBB0_1067

.LBB0_1105:
	s_cmp_gt_i32 s89, 9
	s_cselect_b64 s[2:3], -1, 0
	s_and_b64 s[0:1], s[0:1], s[2:3]
	s_andn2_b64 vcc, exec, s[0:1]
	s_cbranch_vccnz .LBB0_1123
	s_waitcnt vmcnt(0)
	v_cmp_eq_u32_e32 vcc, 0, v0
	s_waitcnt vmcnt(0)
	s_barrier
	s_and_saveexec_b64 s[0:1], vcc
	s_cbranch_execz .LBB0_1122
	v_readlane_b32 s4, v253, 9
	s_lshl_b32 s4, s4, 8
	v_readlane_b32 s6, v253, 3
	v_readlane_b32 s7, v253, 4
	s_add_u32 s4, s6, s4
	s_addc_u32 s5, s7, 0
	v_mov_b32_e32 v1, 0x3000
	v_mov_b32_e32 v2, 1
	s_waitcnt vmcnt(0) expcnt(0) lgkmcnt(0)
	global_atomic_add v4, v1, v2, s[4:5] offset:1792 sc0
	buffer_inv sc1
	s_add_u32 s6, s4, 0x4700
	s_addc_u32 s7, s5, 0
	s_mov_b64 s[8:9], -1
	v_mov_b64_e32 v[2:3], s[6:7]
	s_waitcnt vmcnt(1)
	v_and_b32_e32 v1, 31, v4
	v_cmp_ne_u32_e32 vcc, 31, v1
	s_and_saveexec_b64 s[4:5], vcc
	s_cbranch_execz .LBB0_1119
	v_mov_b32_e32 v1, 0
	global_load_dword v3, v1, s[6:7] sc1
	v_lshrrev_b32_e32 v2, 5, v4
	s_mov_b64 s[12:13], 0
	s_waitcnt vmcnt(0)
	v_cmp_eq_u32_e32 vcc, v3, v2
	s_and_saveexec_b64 s[10:11], vcc
	s_cbranch_execz .LBB0_1118
	s_add_u32 s8, s78, 0x4200
	s_addc_u32 s9, s79, 0
	s_mov_b32 s22, 1
	s_branch .LBB0_1111

.LBB0_1140:
	s_cmp_gt_i32 s89, 10
	s_cselect_b64 s[0:1], -1, 0
	s_and_b64 s[2:3], s[6:7], s[0:1]
	s_andn2_b64 vcc, exec, s[2:3]
	s_cbranch_vccnz .LBB0_1158
	s_waitcnt vmcnt(0)
	v_cmp_eq_u32_e32 vcc, 0, v0
	s_waitcnt vmcnt(0)
	s_barrier
	s_and_saveexec_b64 s[2:3], vcc
	s_cbranch_execz .LBB0_1157
	v_readlane_b32 s4, v253, 9
	s_lshl_b32 s4, s4, 8
	v_readlane_b32 s6, v253, 3
	v_readlane_b32 s7, v253, 4
	s_add_u32 s4, s6, s4
	s_addc_u32 s5, s7, 0
	v_mov_b32_e32 v1, 0x3000
	v_mov_b32_e32 v2, 1
	s_waitcnt vmcnt(0) expcnt(0) lgkmcnt(0)
	global_atomic_add v4, v1, v2, s[4:5] offset:1792 sc0
	buffer_inv sc1
	s_add_u32 s6, s4, 0x4700
	s_addc_u32 s7, s5, 0
	s_mov_b64 s[8:9], -1
	v_mov_b64_e32 v[2:3], s[6:7]
	s_waitcnt vmcnt(1)
	v_and_b32_e32 v1, 31, v4
	v_cmp_ne_u32_e32 vcc, 31, v1
	s_and_saveexec_b64 s[4:5], vcc
	s_cbranch_execz .LBB0_1154
	v_mov_b32_e32 v1, 0
	global_load_dword v3, v1, s[6:7] sc1
	v_lshrrev_b32_e32 v2, 5, v4
	s_mov_b64 s[12:13], 0
	s_waitcnt vmcnt(0)
	v_cmp_eq_u32_e32 vcc, v3, v2
	s_and_saveexec_b64 s[10:11], vcc
	s_cbranch_execz .LBB0_1153
	s_add_u32 s8, s78, 0x4200
	s_addc_u32 s9, s79, 0
	s_mov_b32 s22, 1
	s_branch .LBB0_1146

.LBB0_1202:
	s_cmp_gt_i32 s89, 11
	s_cselect_b64 s[0:1], -1, 0
	v_readlane_b32 s8, v253, 36
	s_and_b64 s[2:3], s[6:7], s[0:1]
	v_readlane_b32 s18, v253, 46
	v_readlane_b32 s19, v253, 47
	s_andn2_b64 vcc, exec, s[2:3]
	s_mov_b64 s[26:27], s[18:19]
	v_readlane_b32 s9, v253, 37
	v_readlane_b32 s10, v253, 38
	v_readlane_b32 s11, v253, 39
	v_readlane_b32 s12, v253, 40
	v_readlane_b32 s13, v253, 41
	v_readlane_b32 s14, v253, 42
	v_readlane_b32 s15, v253, 43
	v_readlane_b32 s16, v253, 44
	v_readlane_b32 s17, v253, 45
	v_readlane_b32 s20, v253, 48
	v_readlane_b32 s21, v253, 49
	v_readlane_b32 s22, v253, 50
	v_readlane_b32 s23, v253, 51
	s_cbranch_vccnz .LBB0_1220
	s_waitcnt vmcnt(0)
	v_cmp_eq_u32_e32 vcc, 0, v0
	s_waitcnt vmcnt(0)
	s_barrier
	s_and_saveexec_b64 s[2:3], vcc
	s_cbranch_execz .LBB0_1219
	v_readlane_b32 s6, v253, 9
	s_lshl_b32 s6, s6, 8
	v_readlane_b32 s8, v253, 3
	v_readlane_b32 s9, v253, 4
	s_add_u32 s6, s8, s6
	s_addc_u32 s7, s9, 0
	v_mov_b32_e32 v1, 0x3000
	v_mov_b32_e32 v2, 1
	s_waitcnt vmcnt(0) expcnt(0) lgkmcnt(0)
	global_atomic_add v4, v1, v2, s[6:7] offset:1792 sc0
	buffer_inv sc1
	s_add_u32 s8, s6, 0x4700
	s_addc_u32 s9, s7, 0
	s_mov_b64 s[10:11], -1
	v_mov_b64_e32 v[2:3], s[8:9]
	s_waitcnt vmcnt(1)
	v_and_b32_e32 v1, 31, v4
	v_cmp_ne_u32_e32 vcc, 31, v1
	s_and_saveexec_b64 s[6:7], vcc
	s_cbranch_execz .LBB0_1216
	v_mov_b32_e32 v1, 0
	global_load_dword v3, v1, s[8:9] sc1
	v_lshrrev_b32_e32 v2, 5, v4
	s_mov_b64 s[14:15], 0
	s_waitcnt vmcnt(0)
	v_cmp_eq_u32_e32 vcc, v3, v2
	s_and_saveexec_b64 s[12:13], vcc
	s_cbranch_execz .LBB0_1215
	s_add_u32 s10, s78, 0x4200
	s_addc_u32 s11, s79, 0
	s_mov_b32 s24, 1
	s_branch .LBB0_1208

.LBB0_1218:
	s_or_b64 exec, exec, s[6:7]
	s_waitcnt vmcnt(0)
	s_waitcnt vmcnt(0)

.LBB0_1246:
	s_cmp_gt_i32 s89, 12
	s_cselect_b64 s[2:3], -1, 0
	s_and_b64 s[0:1], s[0:1], s[2:3]
	s_andn2_b64 vcc, exec, s[0:1]
	s_cbranch_vccnz .LBB0_1264
	s_waitcnt vmcnt(0)
	v_cmp_eq_u32_e32 vcc, 0, v0
	s_waitcnt vmcnt(0)
	s_barrier
	s_and_saveexec_b64 s[0:1], vcc
	s_cbranch_execz .LBB0_1263
	v_readlane_b32 s4, v253, 9
	s_lshl_b32 s4, s4, 8
	v_readlane_b32 s6, v253, 3
	v_readlane_b32 s7, v253, 4
	s_add_u32 s4, s6, s4
	s_addc_u32 s5, s7, 0
	v_mov_b32_e32 v1, 0x3000
	v_mov_b32_e32 v2, 1
	s_waitcnt vmcnt(0) expcnt(0) lgkmcnt(0)
	global_atomic_add v4, v1, v2, s[4:5] offset:1792 sc0
	buffer_inv sc1
	s_add_u32 s6, s4, 0x4700
	s_addc_u32 s7, s5, 0
	s_mov_b64 s[8:9], -1
	v_mov_b64_e32 v[2:3], s[6:7]
	s_waitcnt vmcnt(1)
	v_and_b32_e32 v1, 31, v4
	v_cmp_ne_u32_e32 vcc, 31, v1
	s_and_saveexec_b64 s[4:5], vcc
	s_cbranch_execz .LBB0_1260
	v_mov_b32_e32 v1, 0
	global_load_dword v3, v1, s[6:7] sc1
	v_lshrrev_b32_e32 v2, 5, v4
	s_mov_b64 s[12:13], 0
	s_waitcnt vmcnt(0)
	v_cmp_eq_u32_e32 vcc, v3, v2
	s_and_saveexec_b64 s[10:11], vcc
	s_cbranch_execz .LBB0_1259
	s_add_u32 s8, s78, 0x4200
	s_addc_u32 s9, s79, 0
	s_mov_b32 s22, 1
	s_branch .LBB0_1252

.LBB0_1274:
	s_cmp_gt_i32 s89, 13
	s_cselect_b64 s[0:1], -1, 0
	s_and_b64 s[2:3], s[6:7], s[0:1]
	s_andn2_b64 vcc, exec, s[2:3]
	s_cbranch_vccnz .LBB0_1292
	s_waitcnt vmcnt(0)
	v_cmp_eq_u32_e32 vcc, 0, v0
	s_waitcnt vmcnt(0) lgkmcnt(0)
	s_barrier
	s_and_saveexec_b64 s[2:3], vcc
	s_cbranch_execz .LBB0_1291
	v_readlane_b32 s4, v253, 9
	s_lshl_b32 s4, s4, 8
	v_readlane_b32 s6, v253, 3
	v_readlane_b32 s7, v253, 4
	s_add_u32 s4, s6, s4
	s_addc_u32 s5, s7, 0
	v_mov_b32_e32 v1, 0x3000
	v_mov_b32_e32 v2, 1
	s_waitcnt vmcnt(0) expcnt(0) lgkmcnt(0)
	global_atomic_add v4, v1, v2, s[4:5] offset:1792 sc0
	buffer_inv sc1
	s_add_u32 s6, s4, 0x4700
	s_addc_u32 s7, s5, 0
	s_mov_b64 s[8:9], -1
	v_mov_b64_e32 v[2:3], s[6:7]
	s_waitcnt vmcnt(1)
	v_and_b32_e32 v1, 31, v4
	v_cmp_ne_u32_e32 vcc, 31, v1
	s_and_saveexec_b64 s[4:5], vcc
	s_cbranch_execz .LBB0_1288
	v_mov_b32_e32 v1, 0
	global_load_dword v3, v1, s[6:7] sc1
	v_lshrrev_b32_e32 v2, 5, v4
	s_mov_b64 s[12:13], 0
	s_waitcnt vmcnt(0)
	v_cmp_eq_u32_e32 vcc, v3, v2
	s_and_saveexec_b64 s[10:11], vcc
	s_cbranch_execz .LBB0_1287
	s_add_u32 s8, s78, 0x4200
	s_addc_u32 s9, s79, 0
	s_mov_b32 s22, 1
	s_branch .LBB0_1280

.LBB0_1360:
	s_and_b64 vcc, exec, s[2:3]
	s_cbranch_vccz .LBB0_1378
	s_waitcnt vmcnt(0)
	s_waitcnt vmcnt(0) lgkmcnt(0)
	s_barrier
	s_and_saveexec_b64 s[2:3], s[0:1]
	s_cbranch_execz .LBB0_1377
	v_readlane_b32 s0, v253, 9
	s_lshl_b32 s0, s0, 8
	v_readlane_b32 s6, v253, 3
	v_readlane_b32 s7, v253, 4
	s_add_u32 s0, s6, s0
	s_addc_u32 s1, s7, 0
	v_mov_b32_e32 v2, 0x3000
	v_mov_b32_e32 v3, 1
	s_waitcnt vmcnt(0) expcnt(0) lgkmcnt(0)
	global_atomic_add v4, v2, v3, s[0:1] offset:1792 sc0
	buffer_inv sc1
	s_add_u32 s6, s0, 0x4700
	s_addc_u32 s7, s1, 0
	s_mov_b64 s[8:9], -1
	s_waitcnt vmcnt(1)
	v_and_b32_e32 v2, 31, v4
	v_cmp_ne_u32_e32 vcc, 31, v2
	v_mov_b64_e32 v[2:3], s[6:7]
	s_and_saveexec_b64 s[0:1], vcc
	s_cbranch_execz .LBB0_1374
	v_mov_b32_e32 v2, 0
	global_load_dword v5, v2, s[6:7] sc1
	v_lshrrev_b32_e32 v3, 5, v4
	s_mov_b64 s[12:13], 0
	s_waitcnt vmcnt(0)
	v_cmp_eq_u32_e32 vcc, v5, v3
	s_and_saveexec_b64 s[10:11], vcc
	s_cbranch_execz .LBB0_1373
	s_add_u32 s8, s78, 0x4200
	s_addc_u32 s9, s79, 0
	s_mov_b32 s22, 1
	s_branch .LBB0_1366

.LBB0_1407:
	s_cmp_gt_i32 s89, 14
	s_cselect_b64 s[0:1], -1, 0
	s_and_b64 s[2:3], s[4:5], s[0:1]
	s_andn2_b64 vcc, exec, s[2:3]
	s_cbranch_vccnz .LBB0_1425
	s_waitcnt vmcnt(0)
	v_cmp_eq_u32_e32 vcc, 0, v0
	s_waitcnt vmcnt(0) lgkmcnt(0)
	s_barrier
	s_and_saveexec_b64 s[2:3], vcc
	s_cbranch_execz .LBB0_1424
	v_readlane_b32 s4, v253, 9
	s_lshl_b32 s4, s4, 8
	v_readlane_b32 s6, v253, 3
	v_readlane_b32 s7, v253, 4
	s_add_u32 s4, s6, s4
	s_addc_u32 s5, s7, 0
	v_mov_b32_e32 v1, 0x3000
	v_mov_b32_e32 v2, 1
	s_waitcnt vmcnt(0) expcnt(0) lgkmcnt(0)
	global_atomic_add v4, v1, v2, s[4:5] offset:1792 sc0
	buffer_inv sc1
	s_add_u32 s6, s4, 0x4700
	s_addc_u32 s7, s5, 0
	s_mov_b64 s[8:9], -1
	v_mov_b64_e32 v[2:3], s[6:7]
	s_waitcnt vmcnt(1)
	v_and_b32_e32 v1, 31, v4
	v_cmp_ne_u32_e32 vcc, 31, v1
	s_and_saveexec_b64 s[4:5], vcc
	s_cbranch_execz .LBB0_1421
	v_mov_b32_e32 v1, 0
	global_load_dword v3, v1, s[6:7] sc1
	v_lshrrev_b32_e32 v2, 5, v4
	s_mov_b64 s[12:13], 0
	s_waitcnt vmcnt(0)
	v_cmp_eq_u32_e32 vcc, v3, v2
	s_and_saveexec_b64 s[10:11], vcc
	s_cbranch_execz .LBB0_1420
	s_add_u32 s8, s78, 0x4200
	s_addc_u32 s9, s79, 0
	s_mov_b32 s22, 1
	s_branch .LBB0_1413

.LBB0_1451:
	s_cmp_gt_i32 s89, 15
	s_cselect_b64 s[2:3], -1, 0
	s_and_b64 s[0:1], s[0:1], s[2:3]
	s_andn2_b64 vcc, exec, s[0:1]
	s_cbranch_vccnz .LBB0_1469
	s_waitcnt vmcnt(0)
	v_cmp_eq_u32_e32 vcc, 0, v0
	s_waitcnt vmcnt(0) lgkmcnt(0)
	s_barrier
	s_and_saveexec_b64 s[0:1], vcc
	s_cbranch_execz .LBB0_1468
	v_readlane_b32 s4, v253, 9
	s_lshl_b32 s4, s4, 8
	v_readlane_b32 s6, v253, 3
	v_readlane_b32 s7, v253, 4
	s_add_u32 s4, s6, s4
	s_addc_u32 s5, s7, 0
	v_mov_b32_e32 v0, 0x3000
	v_mov_b32_e32 v1, 1
	s_waitcnt vmcnt(0) expcnt(0) lgkmcnt(0)
	global_atomic_add v2, v0, v1, s[4:5] offset:1792 sc0
	buffer_inv sc1
	s_add_u32 s6, s4, 0x4700
	s_addc_u32 s7, s5, 0
	s_mov_b64 s[8:9], -1
	s_waitcnt vmcnt(1)
	v_and_b32_e32 v0, 31, v2
	v_cmp_ne_u32_e32 vcc, 31, v0
	v_mov_b64_e32 v[0:1], s[6:7]
	s_and_saveexec_b64 s[4:5], vcc
	s_cbranch_execz .LBB0_1465
	v_mov_b32_e32 v0, 0
	global_load_dword v3, v0, s[6:7] sc1
	v_lshrrev_b32_e32 v1, 5, v2
	s_mov_b64 s[12:13], 0
	s_waitcnt vmcnt(0)
	v_cmp_eq_u32_e32 vcc, v3, v1
	s_and_saveexec_b64 s[10:11], vcc
	s_cbranch_execz .LBB0_1464
	s_add_u32 s8, s78, 0x4200
	s_addc_u32 s9, s79, 0
	s_mov_b32 s22, 1
	s_branch .LBB0_1457
